# mix queue order: latent attention items handed out before latent hyena items (hyena pass C waits on GEMM1 tail-unit flags)
# speedup vs baseline: 1.0015x; 1.0015x over previous
.LBB0_641:
	s_or_b64 exec, exec, s[36:37]
	v_mov_b32_e32 v0, s1
	s_waitcnt lgkmcnt(0)
	s_barrier
	ds_read_b32 v0, v0
	s_mov_b64 s[36:37], -1
	s_waitcnt lgkmcnt(0)
	v_cmp_le_i32_e32 vcc, s15, v0
	v_readfirstlane_b32 s18, v0
	s_cbranch_vccnz .LBB0_636
	s_cmp_gt_i32 s18, 63
	s_cbranch_scc0 .LBB0_840
	s_lshl_b32 s42, s18, 1
	v_readlane_b32 s19, v251, 54
	s_add_i32 s19, s19, s42
	s_cmpk_lt_u32 s19, 0x200
	s_cselect_b32 s100, 0x100, 0
	s_xor_b32 s19, s19, s100
	s_cmpk_gt_i32 s19, 0xff
	s_cbranch_scc0 .LBB0_775
	s_cmpk_gt_u32 s19, 0x1ff
	s_cbranch_scc0 .LBB0_751
	s_cmpk_gt_u32 s19, 0x3ff
	s_cbranch_scc0 .LBB0_704
	s_cmpk_gt_u32 s19, 0x4ff
	s_cbranch_scc0 .LBB0_696
	s_cmpk_gt_u32 s19, 0x5ff
	s_cbranch_scc0 .LBB0_673
	s_cmpk_gt_u32 s19, 0x6ff
	s_cbranch_scc0 .LBB0_654
	s_cmpk_gt_u32 s19, 0xa3f
	s_cbranch_scc0 .LBB0_651
	s_lshl_b32 s20, s19, 3
	s_and_b32 s20, s20, 0x7fffffc0
	s_add_i32 s70, s20, 0xffffae00
	s_lshl_b32 s20, s19, 8
	v_mov_b32_e32 v2, v189
	s_and_b32 s20, s20, 0x700
	s_lshl_b32 s21, s20, 2
	v_ashrrev_i32_e32 v3, 6, v2
	v_readlane_b32 s22, v252, 45
	v_add_u32_e32 v0, s70, v3
	s_add_u32 s22, s22, s21
	v_readlane_b32 s21, v252, 46
	v_lshlrev_b32_e32 v1, 4, v2
	s_addc_u32 s23, s21, 0
	v_and_b32_e32 v160, 0x3f0, v1
	v_ashrrev_i32_e32 v1, 31, v0
	v_lshl_add_u64 v[4:5], s[22:23], 0, v[160:161]
	v_lshlrev_b64 v[0:1], 13, v[0:1]
	v_lshl_add_u64 v[0:1], v[4:5], 0, v[0:1]
	global_load_dwordx4 v[24:27], v[0:1], off
	s_mov_b64 s[100:101], 0x8000
	v_lshl_add_u64 v[4:5], v[0:1], 0, s[100:101]
	global_load_dwordx4 v[28:31], v[4:5], off
	v_lshl_add_u64 v[4:5], v[4:5], 0, s[100:101]
	global_load_dwordx4 v[32:35], v[4:5], off
	v_lshl_add_u64 v[4:5], v[4:5], 0, s[100:101]
	global_load_dwordx4 v[36:39], v[4:5], off
	v_lshl_add_u64 v[4:5], v[4:5], 0, s[100:101]
	global_load_dwordx4 v[40:43], v[4:5], off
	v_lshl_add_u64 v[4:5], v[4:5], 0, s[100:101]
	global_load_dwordx4 v[44:47], v[4:5], off
	v_lshl_add_u64 v[4:5], v[4:5], 0, s[100:101]
	global_load_dwordx4 v[48:51], v[4:5], off
	v_lshl_add_u64 v[4:5], v[4:5], 0, s[100:101]
	global_load_dwordx4 v[52:55], v[4:5], off
	v_lshl_add_u64 v[4:5], v[4:5], 0, s[100:101]
	global_load_dwordx4 v[56:59], v[4:5], off
	v_lshl_add_u64 v[4:5], v[4:5], 0, s[100:101]
	global_load_dwordx4 v[60:63], v[4:5], off
	v_lshl_add_u64 v[4:5], v[4:5], 0, s[100:101]
	global_load_dwordx4 v[64:67], v[4:5], off
	v_lshl_add_u64 v[4:5], v[4:5], 0, s[100:101]
	global_load_dwordx4 v[68:71], v[4:5], off
	v_lshl_add_u64 v[4:5], v[4:5], 0, s[100:101]
	global_load_dwordx4 v[72:75], v[4:5], off
	v_lshl_add_u64 v[4:5], v[4:5], 0, s[100:101]
	global_load_dwordx4 v[76:79], v[4:5], off
	v_lshl_add_u64 v[4:5], v[4:5], 0, s[100:101]
	global_load_dwordx4 v[80:83], v[4:5], off
	v_lshl_add_u64 v[4:5], v[4:5], 0, s[100:101]
	global_load_dwordx4 v[84:87], v[4:5], off
	s_movk_i32 s36, 0x404
	v_mul_lo_u32 v3, v3, s36
	v_add3_u32 v3, s17, v160, v3
	s_lshl_b64 s[22:23], s[70:71], 1
	v_readlane_b32 s21, v252, 47
	s_nop 0
	s_add_u32 s22, s21, s22
	v_readlane_b32 s21, v252, 48
	s_nop 0
	s_addc_u32 s23, s21, s23
	s_waitcnt vmcnt(15)
	ds_write2_b32 v3, v24, v25 offset1:1
	ds_write2_b32 v3, v26, v27 offset0:2 offset1:3
	s_waitcnt vmcnt(14)
	v_add_u32_e32 v8, 0x1010, v3
	ds_write2_b32 v8, v28, v29 offset1:1
	ds_write2_b32 v8, v30, v31 offset0:2 offset1:3
	s_waitcnt vmcnt(13)
	v_add_u32_e32 v8, 0x2020, v3
	ds_write2_b32 v8, v32, v33 offset1:1
	ds_write2_b32 v8, v34, v35 offset0:2 offset1:3
	s_waitcnt vmcnt(12)
	v_add_u32_e32 v8, 0x3030, v3
	ds_write2_b32 v8, v36, v37 offset1:1
	ds_write2_b32 v8, v38, v39 offset0:2 offset1:3
	s_waitcnt vmcnt(11)
	v_add_u32_e32 v8, 0x4040, v3
	ds_write2_b32 v8, v40, v41 offset1:1
	ds_write2_b32 v8, v42, v43 offset0:2 offset1:3
	s_waitcnt vmcnt(10)
	v_add_u32_e32 v8, 0x5050, v3
	ds_write2_b32 v8, v44, v45 offset1:1
	ds_write2_b32 v8, v46, v47 offset0:2 offset1:3
	s_waitcnt vmcnt(9)
	v_add_u32_e32 v8, 0x6060, v3
	ds_write2_b32 v8, v48, v49 offset1:1
	ds_write2_b32 v8, v50, v51 offset0:2 offset1:3
	s_waitcnt vmcnt(8)
	v_add_u32_e32 v8, 0x7070, v3
	ds_write2_b32 v8, v52, v53 offset1:1
	ds_write2_b32 v8, v54, v55 offset0:2 offset1:3
	s_waitcnt vmcnt(7)
	v_add_u32_e32 v8, 0x8080, v3
	ds_write2_b32 v8, v56, v57 offset1:1
	ds_write2_b32 v8, v58, v59 offset0:2 offset1:3
	s_waitcnt vmcnt(6)
	v_add_u32_e32 v8, 0x9090, v3
	ds_write2_b32 v8, v60, v61 offset1:1
	ds_write2_b32 v8, v62, v63 offset0:2 offset1:3
	s_waitcnt vmcnt(5)
	v_add_u32_e32 v8, 0xa0a0, v3
	ds_write2_b32 v8, v64, v65 offset1:1
	ds_write2_b32 v8, v66, v67 offset0:2 offset1:3
	s_waitcnt vmcnt(4)
	v_add_u32_e32 v8, 0xb0b0, v3
	ds_write2_b32 v8, v68, v69 offset1:1
	ds_write2_b32 v8, v70, v71 offset0:2 offset1:3
	s_waitcnt vmcnt(3)
	v_add_u32_e32 v8, 0xc0c0, v3
	ds_write2_b32 v8, v72, v73 offset1:1
	ds_write2_b32 v8, v74, v75 offset0:2 offset1:3
	s_waitcnt vmcnt(2)
	v_add_u32_e32 v8, 0xd0d0, v3
	ds_write2_b32 v8, v76, v77 offset1:1
	ds_write2_b32 v8, v78, v79 offset0:2 offset1:3
	s_waitcnt vmcnt(1)
	v_add_u32_e32 v8, 0xe0e0, v3
	ds_write2_b32 v8, v80, v81 offset1:1
	ds_write2_b32 v8, v82, v83 offset0:2 offset1:3
	s_waitcnt vmcnt(0)
	v_add_u32_e32 v8, 0xf0f0, v3
	ds_write2_b32 v8, v84, v85 offset1:1
	ds_write2_b32 v8, v86, v87 offset0:2 offset1:3
	v_lshlrev_b32_e32 v0, 3, v2
	v_and_b32_e32 v3, 56, v0
	v_mov_b32_e32 v4, s17
	v_lshlrev_b32_e32 v160, 1, v3
	v_ashrrev_i32_e32 v8, 3, v2
	v_mad_u32_u24 v3, v3, s36, v4
	v_lshl_add_u32 v4, v8, 2, v3
	s_waitcnt lgkmcnt(0)
	s_barrier
	ds_read_b32 v5, v4
	ds_read_b32 v6, v4 offset:1028
	ds_read_b32 v7, v4 offset:2056
	ds_read_b32 v9, v4 offset:3084
	ds_read_b32 v10, v4 offset:4112
	ds_read_b32 v11, v4 offset:5140
	ds_read_b32 v12, v4 offset:6168
	ds_read_b32 v4, v4 offset:7196
	s_waitcnt lgkmcnt(4)
	v_bfe_u32 v20, v5, 16, 1
	v_add3_u32 v20, v5, v20, s94
	v_cvt_pk_bf16_f32 v9, v7, v9
	v_add_u32_e32 v8, s20, v8
	s_waitcnt lgkmcnt(0)
	v_bfe_u32 v19, v6, 16, 1
	v_mov_b32_e32 v5, v9
	v_ashrrev_i32_e32 v9, 31, v8
	v_lshl_add_u64 v[0:1], s[22:23], 0, v[160:161]
	v_add3_u32 v19, v6, v19, s94
	v_cvt_pk_bf16_f32 v10, v10, v11
	v_cvt_pk_bf16_f32 v4, v12, v4
	v_lshlrev_b64 v[8:9], 12, v[8:9]
	v_mov_b32_e32 v7, v4
	v_mov_b32_e32 v6, v10
	v_perm_b32 v4, v19, v20, s95
	v_lshl_add_u64 v[8:9], v[0:1], 0, v[8:9]
	global_store_dwordx4 v[8:9], v[4:7], off
	s_mov_b64 s[36:37], 0
	s_nop 0
	v_add_u32_e32 v4, 0x100, v2
	v_ashrrev_i32_e32 v8, 3, v4
	v_lshl_add_u32 v4, v8, 2, v3
	ds_read_b32 v5, v4
	ds_read_b32 v6, v4 offset:1028
	ds_read_b32 v7, v4 offset:2056
	ds_read_b32 v9, v4 offset:3084
	ds_read_b32 v10, v4 offset:4112
	ds_read_b32 v11, v4 offset:5140
	ds_read_b32 v12, v4 offset:6168
	ds_read_b32 v4, v4 offset:7196
	s_waitcnt lgkmcnt(4)
	v_bfe_u32 v20, v5, 16, 1
	v_add3_u32 v20, v5, v20, s94
	v_cvt_pk_bf16_f32 v9, v7, v9
	v_add_u32_e32 v8, s20, v8
	s_waitcnt lgkmcnt(0)
	v_bfe_u32 v19, v6, 16, 1
	v_mov_b32_e32 v5, v9
	v_ashrrev_i32_e32 v9, 31, v8
	v_add3_u32 v19, v6, v19, s94
	v_cvt_pk_bf16_f32 v10, v10, v11
	v_cvt_pk_bf16_f32 v4, v12, v4
	v_lshlrev_b64 v[8:9], 12, v[8:9]
	v_mov_b32_e32 v7, v4
	v_mov_b32_e32 v6, v10
	v_perm_b32 v4, v19, v20, s95
	v_lshl_add_u64 v[8:9], v[0:1], 0, v[8:9]
	global_store_dwordx4 v[8:9], v[4:7], off
	s_nop 1
	v_add_u32_e32 v4, 0x200, v2
	v_ashrrev_i32_e32 v8, 3, v4
	v_lshl_add_u32 v4, v8, 2, v3
	ds_read_b32 v5, v4
	ds_read_b32 v6, v4 offset:1028
	ds_read_b32 v7, v4 offset:2056
	ds_read_b32 v9, v4 offset:3084
	ds_read_b32 v10, v4 offset:4112
	ds_read_b32 v11, v4 offset:5140
	ds_read_b32 v12, v4 offset:6168
	ds_read_b32 v4, v4 offset:7196
	s_waitcnt lgkmcnt(4)
	v_bfe_u32 v20, v5, 16, 1
	v_add3_u32 v20, v5, v20, s94
	v_cvt_pk_bf16_f32 v9, v7, v9
	v_add_u32_e32 v8, s20, v8
	s_waitcnt lgkmcnt(0)
	v_bfe_u32 v19, v6, 16, 1
	v_mov_b32_e32 v5, v9
	v_ashrrev_i32_e32 v9, 31, v8
	v_add3_u32 v19, v6, v19, s94
	v_cvt_pk_bf16_f32 v10, v10, v11
	v_cvt_pk_bf16_f32 v4, v12, v4
	v_lshlrev_b64 v[8:9], 12, v[8:9]
	v_mov_b32_e32 v7, v4
	v_mov_b32_e32 v6, v10
	v_perm_b32 v4, v19, v20, s95
	v_lshl_add_u64 v[8:9], v[0:1], 0, v[8:9]
	global_store_dwordx4 v[8:9], v[4:7], off
	s_nop 1
	v_add_u32_e32 v4, 0x300, v2
	v_ashrrev_i32_e32 v8, 3, v4
	v_lshl_add_u32 v4, v8, 2, v3
	ds_read_b32 v5, v4
	ds_read_b32 v6, v4 offset:1028
	ds_read_b32 v7, v4 offset:2056
	ds_read_b32 v9, v4 offset:3084
	ds_read_b32 v10, v4 offset:4112
	ds_read_b32 v11, v4 offset:5140
	ds_read_b32 v12, v4 offset:6168
	ds_read_b32 v4, v4 offset:7196
	s_waitcnt lgkmcnt(4)
	v_bfe_u32 v20, v5, 16, 1
	v_add3_u32 v20, v5, v20, s94
	v_cvt_pk_bf16_f32 v9, v7, v9
	v_add_u32_e32 v8, s20, v8
	s_waitcnt lgkmcnt(0)
	v_bfe_u32 v19, v6, 16, 1
	v_mov_b32_e32 v5, v9
	v_ashrrev_i32_e32 v9, 31, v8
	v_add3_u32 v19, v6, v19, s94
	v_cvt_pk_bf16_f32 v10, v10, v11
	v_cvt_pk_bf16_f32 v4, v12, v4
	v_lshlrev_b64 v[8:9], 12, v[8:9]
	v_mov_b32_e32 v7, v4
	v_mov_b32_e32 v6, v10
	v_perm_b32 v4, v19, v20, s95
	v_lshl_add_u64 v[8:9], v[0:1], 0, v[8:9]
	global_store_dwordx4 v[8:9], v[4:7], off
	s_nop 1
	v_add_u32_e32 v4, 0x400, v2
	v_ashrrev_i32_e32 v8, 3, v4
	v_lshl_add_u32 v4, v8, 2, v3
	ds_read_b32 v5, v4
	ds_read_b32 v6, v4 offset:1028
	ds_read_b32 v7, v4 offset:2056
	ds_read_b32 v9, v4 offset:3084
	ds_read_b32 v10, v4 offset:4112
	ds_read_b32 v11, v4 offset:5140
	ds_read_b32 v12, v4 offset:6168
	ds_read_b32 v4, v4 offset:7196
	s_waitcnt lgkmcnt(4)
	v_bfe_u32 v20, v5, 16, 1
	v_add3_u32 v20, v5, v20, s94
	v_cvt_pk_bf16_f32 v9, v7, v9
	v_add_u32_e32 v8, s20, v8
	s_waitcnt lgkmcnt(0)
	v_bfe_u32 v19, v6, 16, 1
	v_mov_b32_e32 v5, v9
	v_ashrrev_i32_e32 v9, 31, v8
	v_add3_u32 v19, v6, v19, s94
	v_cvt_pk_bf16_f32 v10, v10, v11
	v_cvt_pk_bf16_f32 v4, v12, v4
	v_lshlrev_b64 v[8:9], 12, v[8:9]
	v_mov_b32_e32 v7, v4
	v_mov_b32_e32 v6, v10
	v_perm_b32 v4, v19, v20, s95
	v_lshl_add_u64 v[8:9], v[0:1], 0, v[8:9]
	global_store_dwordx4 v[8:9], v[4:7], off
	s_nop 1
	v_add_u32_e32 v4, 0x500, v2
	v_ashrrev_i32_e32 v8, 3, v4
	v_lshl_add_u32 v4, v8, 2, v3
	ds_read_b32 v5, v4
	ds_read_b32 v6, v4 offset:1028
	ds_read_b32 v7, v4 offset:2056
	ds_read_b32 v9, v4 offset:3084
	ds_read_b32 v10, v4 offset:4112
	ds_read_b32 v11, v4 offset:5140
	ds_read_b32 v12, v4 offset:6168
	ds_read_b32 v4, v4 offset:7196
	s_waitcnt lgkmcnt(4)
	v_bfe_u32 v20, v5, 16, 1
	v_add3_u32 v20, v5, v20, s94
	v_cvt_pk_bf16_f32 v9, v7, v9
	v_add_u32_e32 v8, s20, v8
	s_waitcnt lgkmcnt(0)
	v_bfe_u32 v19, v6, 16, 1
	v_mov_b32_e32 v5, v9
	v_ashrrev_i32_e32 v9, 31, v8
	v_add3_u32 v19, v6, v19, s94
	v_cvt_pk_bf16_f32 v10, v10, v11
	v_cvt_pk_bf16_f32 v4, v12, v4
	v_lshlrev_b64 v[8:9], 12, v[8:9]
	v_mov_b32_e32 v7, v4
	v_mov_b32_e32 v6, v10
	v_perm_b32 v4, v19, v20, s95
	v_lshl_add_u64 v[8:9], v[0:1], 0, v[8:9]
	global_store_dwordx4 v[8:9], v[4:7], off
	s_nop 1
	v_add_u32_e32 v4, 0x600, v2
	v_ashrrev_i32_e32 v8, 3, v4
	v_lshl_add_u32 v4, v8, 2, v3
	ds_read_b32 v5, v4
	ds_read_b32 v6, v4 offset:1028
	ds_read_b32 v7, v4 offset:2056
	ds_read_b32 v9, v4 offset:3084
	ds_read_b32 v10, v4 offset:4112
	ds_read_b32 v11, v4 offset:5140
	ds_read_b32 v12, v4 offset:6168
	ds_read_b32 v4, v4 offset:7196
	s_waitcnt lgkmcnt(4)
	v_bfe_u32 v20, v5, 16, 1
	v_add3_u32 v20, v5, v20, s94
	v_cvt_pk_bf16_f32 v9, v7, v9
	v_add_u32_e32 v8, s20, v8
	s_waitcnt lgkmcnt(0)
	v_bfe_u32 v19, v6, 16, 1
	v_mov_b32_e32 v5, v9
	v_ashrrev_i32_e32 v9, 31, v8
	v_add3_u32 v19, v6, v19, s94
	v_cvt_pk_bf16_f32 v10, v10, v11
	v_cvt_pk_bf16_f32 v4, v12, v4
	v_lshlrev_b64 v[8:9], 12, v[8:9]
	v_mov_b32_e32 v7, v4
	v_mov_b32_e32 v6, v10
	v_perm_b32 v4, v19, v20, s95
	v_lshl_add_u64 v[8:9], v[0:1], 0, v[8:9]
	v_add_u32_e32 v2, 0x700, v2
	global_store_dwordx4 v[8:9], v[4:7], off
	s_nop 1
	v_ashrrev_i32_e32 v6, 3, v2
	v_lshl_add_u32 v2, v6, 2, v3
	ds_read_b32 v3, v2
	ds_read_b32 v4, v2 offset:1028
	ds_read_b32 v5, v2 offset:2056
	ds_read_b32 v7, v2 offset:3084
	ds_read_b32 v8, v2 offset:4112
	ds_read_b32 v9, v2 offset:5140
	ds_read_b32 v10, v2 offset:6168
	ds_read_b32 v2, v2 offset:7196
	s_waitcnt lgkmcnt(4)
	v_bfe_u32 v18, v3, 16, 1
	v_add3_u32 v18, v3, v18, s94
	v_cvt_pk_bf16_f32 v7, v5, v7
	v_add_u32_e32 v6, s20, v6
	s_waitcnt lgkmcnt(0)
	v_bfe_u32 v17, v4, 16, 1
	v_mov_b32_e32 v3, v7
	v_ashrrev_i32_e32 v7, 31, v6
	v_add3_u32 v17, v4, v17, s94
	v_cvt_pk_bf16_f32 v8, v8, v9
	v_cvt_pk_bf16_f32 v2, v10, v2
	v_lshlrev_b64 v[6:7], 12, v[6:7]
	v_mov_b32_e32 v5, v2
	v_mov_b32_e32 v4, v8
	v_perm_b32 v2, v17, v18, s95
	v_lshl_add_u64 v[0:1], v[0:1], 0, v[6:7]
	global_store_dwordx4 v[0:1], v[2:5], off
	s_barrier
